# attention: static priority 2 for waves 4-7 (younger half of each SIMD pair), others keep priority 1
# speedup vs baseline: 1.0059x; 1.0059x over previous
; #define GAS __attribute__((address_space(1)))
; #define AT_KRD(dst, koff, ks0) do { const LAS unsigned char* Kl = Kr + (koff); \
;             _Pragma("unroll") for (int ks = 0; ks < 3; ++ks) { dst[2 * ks] = *(const LAS bf16x8_t*)(Kl + ((ks0) + ks) * 32); dst[2 * ks + 1] = *(const LAS bf16x8_t*)(Kl + 32 * AT_KP + ((ks0) + ks) * 32); } } while (0)
; #define AT_KMM(P0, P1, src, ks0) do { _Pragma("unroll") for (int ks = 0; ks < 3; ++ks) { \
;             P0 = __builtin_amdgcn_mfma_f32_32x32x16_bf16(src[2 * ks], qf[(ks0) + ks], P0, 0, 0, 0); P1 = __builtin_amdgcn_mfma_f32_32x32x16_bf16(src[2 * ks + 1], qf[(ks0) + ks], P1, 0, 0, 0); } } while (0)
; #define AT_ZERO(P0, P1) do { _Pragma("unroll") for (int r = 0; r < 16; ++r) { P0[r] = 0.f; P1[r] = 0.f; } } while (0)
; __device__ __forceinline__ void ph_attn(Frame& F) {
;     ...
;         bf16x8_t qf[6];
;         { const bf16* qp = Qb + (bh * TQK + tq0 + wave * 32 + r32) * 96 + hi * 8;
; #pragma unroll
;           for (int ks = 0; ks < 6; ++ks) qf[ks] = *(const GAS bf16x8_t*)(qp + ks * 16); }
;         f32x16 o0, o1, pA0, pA1, pB0, pB1;
;         bf16x8_t pk0, pk1, pk2_, pk3;
;         bf16x8_t vf[8], kf[6];
;         { const v4u z = (v4u){0u, 0u, 0u, 0u}; pk0 = __builtin_bit_cast(bf16x8_t, z); pk1 = pk0; pk2_ = pk0; pk3 = pk0;
; #pragma unroll
;           for (int j = 0; j < 8; ++j) vf[j] = pk0; }
; #pragma unroll
;         for (int r = 0; r < 16; ++r) { o0[r] = 0.f; o1[r] = 0.f; pB0[r] = 0.f; pB1[r] = 0.f; }
;         float m_run = -1e30f, l_run = 0.f;
;     ...
;         asm volatile("s_waitcnt vmcnt(0)" ::: "memory");
;         __syncthreads();
;         AT_DMA(0, 0, 0, 0); AT_DMA(1, AT_KB, 1, AT_VB); AT_DMA(2, 2 * AT_KB, 0, 0); AT_DMA(3, 3 * AT_KB, 1, AT_VB);
;         asm volatile("s_waitcnt vmcnt(0)" ::: "memory");
;         __syncthreads();
;     ...
;         int kq = AT_KB, kn = 2 * AT_KB, k3 = 3 * AT_KB, kw = 0, vn = 0, v1 = AT_VB, vw = 2 * AT_VB;
;         { bf16x8_t kg[6]; AT_KRD(kf, 0, 0); AT_KRD(kg, 0, 3); AT_ZERO(pA0, pA1); AT_KMM(pA0, pA1, kf, 0); AT_KMM(pA0, pA1, kg, 3); AT_KRD(kf, AT_KB, 0); }
;         __syncthreads();
;         if (AT_PRIO && __builtin_amdgcn_readfirstlane(wave) >= 4) __builtin_amdgcn_s_setprio(1);
.LBB0_996:
	s_and_b32 s35, s13, 7
	s_lshl_b32 s11, s12, 3
	s_or_b32 s11, s11, s35
	v_add_u32_e32 v2, s10, v201
	s_mul_hi_i32 s12, s11, 0x18c000
	s_mul_i32 s13, s11, 0x18c000
	s_mul_hi_i32 s14, s11, 0x108000
	s_mul_i32 s15, s11, 0x108000
	v_mad_i64_i32 v[4:5], s[10:11], s11, v207, v[2:3]
	v_mad_u64_u32 v[6:7], s[10:11], v4, s20, v[196:197]
	v_mad_i32_i24 v7, v5, s20, v7
	global_load_dwordx4 v[100:103], v[6:7], off
	global_load_dwordx4 v[104:107], v[6:7], off offset:32
	global_load_dwordx4 v[108:111], v[6:7], off offset:64
	global_load_dwordx4 v[112:115], v[6:7], off offset:96
	global_load_dwordx4 v[116:119], v[6:7], off offset:128
	global_load_dwordx4 v[120:123], v[6:7], off offset:160
	s_add_u32 s10, s16, s13
	s_addc_u32 s11, s17, s12
	s_add_u32 s12, s18, s15
	s_addc_u32 s13, s19, s14
	s_and_b64 s[14:15], s[4:5], exec
	s_mov_b32 m0, s22
	v_lshl_add_u64 v[4:5], s[10:11], 0, v[190:191]
	s_cselect_b32 s15, s11, s13
	s_cselect_b32 s14, s10, s12
	s_waitcnt vmcnt(6)
	s_barrier
	global_load_lds_dwordx4 v[4:5], off
	v_lshl_add_u64 v[4:5], s[14:15], 0, v[192:193]
	s_add_u32 s14, s10, 0x3000
	s_addc_u32 s15, s11, 0
	s_add_u32 s38, s12, 0x2000
	s_mov_b32 m0, s21
	s_addc_u32 s39, s13, 0
	global_load_lds_dwordx4 v[4:5], off
	v_lshl_add_u64 v[4:5], s[12:13], 0, v[194:195]
	s_mov_b32 m0, s31
	s_and_b64 s[40:41], s[4:5], exec
	global_load_lds_dwordx4 v[4:5], off
	v_lshl_add_u64 v[6:7], s[14:15], 0, v[190:191]
	s_mov_b32 m0, s24
	s_cselect_b32 s15, s15, s39
	s_cselect_b32 s14, s14, s38
	global_load_lds_dwordx4 v[6:7], off
	v_lshl_add_u64 v[6:7], s[14:15], 0, v[192:193]
	s_add_u32 s14, s10, 0x6000
	s_mov_b32 m0, s25
	s_addc_u32 s15, s11, 0
	global_load_lds_dwordx4 v[6:7], off
	v_lshl_add_u64 v[6:7], s[38:39], 0, v[194:195]
	s_mov_b32 m0, s26
	s_and_b64 s[40:41], s[4:5], exec
	global_load_lds_dwordx4 v[6:7], off
	v_lshl_add_u64 v[8:9], s[14:15], 0, v[190:191]
	s_mov_b32 m0, s27
	s_cselect_b32 s15, s15, s13
	s_cselect_b32 s14, s14, s12
	global_load_lds_dwordx4 v[8:9], off
	v_lshl_add_u64 v[8:9], s[14:15], 0, v[192:193]
	s_add_u32 s14, s10, 0x9000
	s_mov_b32 m0, s28
	s_addc_u32 s15, s11, 0
	global_load_lds_dwordx4 v[8:9], off
	s_mov_b32 m0, s31
	s_and_b64 s[40:41], s[4:5], exec
	global_load_lds_dwordx4 v[4:5], off
	v_lshl_add_u64 v[4:5], s[14:15], 0, v[190:191]
	s_mov_b32 m0, s29
	s_cselect_b32 s15, s15, s39
	s_cselect_b32 s14, s14, s38
	global_load_lds_dwordx4 v[4:5], off
	v_lshl_add_u64 v[4:5], s[14:15], 0, v[192:193]
	s_mov_b32 m0, s30
	v_readfirstlane_b32 s14, v206
	global_load_lds_dwordx4 v[4:5], off
	s_mov_b32 m0, s26
	s_cmp_lt_i32 s14, 4
	global_load_lds_dwordx4 v[6:7], off
	s_waitcnt vmcnt(0)
	s_waitcnt vmcnt(0) lgkmcnt(0)
	s_barrier
	ds_read_b128 v[4:7], v189
	ds_read_b128 v[8:11], v189 offset:32
	s_waitcnt lgkmcnt(1)
	v_mfma_f32_32x32x16_bf16 v[52:67], v[4:7], v[100:103], 0
	ds_read_b128 v[4:7], v189 offset:6656
	ds_read_b128 v[12:15], v189 offset:6688
	s_waitcnt lgkmcnt(1)
	v_mfma_f32_32x32x16_bf16 v[36:51], v[4:7], v[100:103], 0
	v_mfma_f32_32x32x16_bf16 v[52:67], v[8:11], v[104:107], v[52:67]
	ds_read_b128 v[4:7], v189 offset:64
	ds_read_b128 v[8:11], v189 offset:96
	s_waitcnt lgkmcnt(2)
	v_mfma_f32_32x32x16_bf16 v[36:51], v[12:15], v[104:107], v[36:51]
	s_waitcnt lgkmcnt(1)
	v_mfma_f32_32x32x16_bf16 v[52:67], v[4:7], v[108:111], v[52:67]
	ds_read_b128 v[4:7], v189 offset:6720
	ds_read_b128 v[12:15], v189 offset:6752
	s_waitcnt lgkmcnt(1)
	v_mfma_f32_32x32x16_bf16 v[36:51], v[4:7], v[108:111], v[36:51]
	s_waitcnt lgkmcnt(0)
	v_mfma_f32_32x32x16_bf16 v[36:51], v[12:15], v[112:115], v[36:51]
	v_mfma_f32_32x32x16_bf16 v[52:67], v[8:11], v[112:115], v[52:67]
	ds_read_b128 v[4:7], v189 offset:6784
	ds_read_b128 v[8:11], v189 offset:6816
	s_waitcnt lgkmcnt(1)
	v_mfma_f32_32x32x16_bf16 v[36:51], v[4:7], v[116:119], v[36:51]
	ds_read_b128 v[4:7], v189 offset:128
	ds_read_b128 v[12:15], v189 offset:160
	ds_read_b128 v[132:135], v189 offset:13312
	ds_read_b128 v[128:131], v189 offset:13344
	ds_read_b128 v[136:139], v189 offset:19968
	ds_read_b128 v[124:127], v189 offset:13376
	ds_read_b128 v[144:147], v189 offset:20000
	ds_read_b128 v[140:143], v189 offset:20032
	s_waitcnt lgkmcnt(0)
	s_barrier
	v_mfma_f32_32x32x16_bf16 v[52:67], v[4:7], v[116:119], v[52:67]
	v_mfma_f32_32x32x16_bf16 v[36:51], v[8:11], v[120:123], v[36:51]
	v_mfma_f32_32x32x16_bf16 v[52:67], v[12:15], v[120:123], v[52:67]
	s_cbranch_scc1 .LBB0_998
	v_readfirstlane_b32 s99, v236
	s_lshr_b32 s99, s99, 8
	s_cmp_lg_u32 s99, 0
	s_cbranch_scc1 .Lprio_young
	s_setprio 1
	s_branch .LBB0_998
.Lprio_young:
	s_setprio 2
